# P1-transpose-loads-unrolled
# baseline (speedup 1.0000x reference)
; #define LAS __attribute__((address_space(3)))
; __device__ __forceinline__ unsigned pk2(float lo, float hi) { const f32x2 v = {lo, hi}; return __builtin_bit_cast(unsigned, __builtin_convertvector(v, bf16x2_hw)); }
; #pragma unroll 8
;     for (int i = 0; i < 32; ++i) { const int kk = 2 * i + (lane >> 5); scr[kk * 33 + (lane & 31)] = __builtin_nontemporal_load(&W[(size_t)(k0 + kk) * ldw + col0 + n0 + (lane & 31)]); }
;     asm volatile("s_waitcnt lgkmcnt(0)" ::: "memory");
;     const int c = lane & 7;
; #pragma unroll
;     for (int j = 0; j < 4; ++j) { const int n = (lane >> 3) + 8 * j; const LAS float* s = scr + (8 * c) * 33 + n;
;         u32x4 o; o.x = pk2(s[0 * 33], s[1 * 33]); o.y = pk2(s[2 * 33], s[3 * 33]); o.z = pk2(s[4 * 33], s[5 * 33]); o.w = pk2(s[6 * 33], s[7 * 33]);
;         const int drow = perm ? (drow0 + 8 * (n >> 2) + (n & 3) + (d0 ? 4 : 0)) : (drow0 + n);
;         *(u32x4*)(WT + (size_t)drow * K + k0 + 8 * c) = o; }
;     asm volatile("s_waitcnt lgkmcnt(0)" ::: "memory");
.LBB0_114:
	v_lshl_add_u64 v[54:55], v[26:27], 0, s[4:5]
	v_lshl_add_u64 v[56:57], v[24:25], 0, s[4:5]
	v_lshl_add_u64 v[58:59], v[22:23], 0, s[4:5]
	v_lshl_add_u64 v[60:61], v[20:21], 0, s[4:5]
	v_lshl_add_u64 v[62:63], v[18:19], 0, s[4:5]
	v_lshl_add_u64 v[64:65], v[16:17], 0, s[4:5]
	v_lshl_add_u64 v[66:67], v[14:15], 0, s[4:5]
	v_lshl_add_u64 v[68:69], v[12:13], 0, s[4:5]
	global_load_dword v77, v[54:55], off nt
	global_load_dword v78, v[56:57], off nt
	global_load_dword v79, v[58:59], off nt
	global_load_dword v80, v[60:61], off nt
	global_load_dword v81, v[62:63], off nt
	global_load_dword v82, v[64:65], off nt
	global_load_dword v83, v[66:67], off nt
	global_load_dword v84, v[68:69], off nt
	s_add_u32 s4, s4, 0x74400
	s_addc_u32 s5, s5, 0
	v_lshl_add_u64 v[54:55], v[26:27], 0, s[4:5]
	v_lshl_add_u64 v[56:57], v[24:25], 0, s[4:5]
	v_lshl_add_u64 v[58:59], v[22:23], 0, s[4:5]
	v_lshl_add_u64 v[60:61], v[20:21], 0, s[4:5]
	v_lshl_add_u64 v[62:63], v[18:19], 0, s[4:5]
	v_lshl_add_u64 v[64:65], v[16:17], 0, s[4:5]
	v_lshl_add_u64 v[66:67], v[14:15], 0, s[4:5]
	v_lshl_add_u64 v[68:69], v[12:13], 0, s[4:5]
	global_load_dword v85, v[54:55], off nt
	global_load_dword v86, v[56:57], off nt
	global_load_dword v87, v[58:59], off nt
	global_load_dword v88, v[60:61], off nt
	global_load_dword v89, v[62:63], off nt
	global_load_dword v90, v[64:65], off nt
	global_load_dword v91, v[66:67], off nt
	global_load_dword v92, v[68:69], off nt
	s_add_u32 s4, s4, 0x74400
	s_addc_u32 s5, s5, 0
	v_lshl_add_u64 v[54:55], v[26:27], 0, s[4:5]
	v_lshl_add_u64 v[56:57], v[24:25], 0, s[4:5]
	v_lshl_add_u64 v[58:59], v[22:23], 0, s[4:5]
	v_lshl_add_u64 v[60:61], v[20:21], 0, s[4:5]
	v_lshl_add_u64 v[62:63], v[18:19], 0, s[4:5]
	v_lshl_add_u64 v[64:65], v[16:17], 0, s[4:5]
	v_lshl_add_u64 v[66:67], v[14:15], 0, s[4:5]
	v_lshl_add_u64 v[68:69], v[12:13], 0, s[4:5]
	global_load_dword v93, v[54:55], off nt
	global_load_dword v94, v[56:57], off nt
	global_load_dword v95, v[58:59], off nt
	global_load_dword v96, v[60:61], off nt
	global_load_dword v97, v[62:63], off nt
	global_load_dword v98, v[64:65], off nt
	global_load_dword v99, v[66:67], off nt
	global_load_dword v100, v[68:69], off nt
	s_add_u32 s4, s4, 0x74400
	s_addc_u32 s5, s5, 0
	v_lshl_add_u64 v[54:55], v[26:27], 0, s[4:5]
	v_lshl_add_u64 v[56:57], v[24:25], 0, s[4:5]
	v_lshl_add_u64 v[58:59], v[22:23], 0, s[4:5]
	v_lshl_add_u64 v[60:61], v[20:21], 0, s[4:5]
	v_lshl_add_u64 v[62:63], v[18:19], 0, s[4:5]
	v_lshl_add_u64 v[64:65], v[16:17], 0, s[4:5]
	v_lshl_add_u64 v[66:67], v[14:15], 0, s[4:5]
	v_lshl_add_u64 v[68:69], v[12:13], 0, s[4:5]
	global_load_dword v101, v[54:55], off nt
	global_load_dword v102, v[56:57], off nt
	global_load_dword v103, v[58:59], off nt
	global_load_dword v104, v[60:61], off nt
	global_load_dword v105, v[62:63], off nt
	global_load_dword v106, v[64:65], off nt
	global_load_dword v107, v[66:67], off nt
	global_load_dword v108, v[68:69], off nt
	s_add_u32 s4, s4, 0x74400
	s_addc_u32 s5, s5, 0
	v_add_u32_e32 v54, 0x400, v52
	s_waitcnt vmcnt(30)
	ds_write2_b32 v52, v77, v78 offset1:66
	s_waitcnt vmcnt(28)
	ds_write2_b32 v52, v79, v80 offset0:132 offset1:198
	s_waitcnt vmcnt(26)
	ds_write2_b32 v54, v81, v82 offset0:8 offset1:74
	s_waitcnt vmcnt(24)
	ds_write2_b32 v54, v83, v84 offset0:140 offset1:206
	v_add_u32_e32 v52, 0x840, v52
	v_add_u32_e32 v54, 0x400, v52
	s_waitcnt vmcnt(22)
	ds_write2_b32 v52, v85, v86 offset1:66
	s_waitcnt vmcnt(20)
	ds_write2_b32 v52, v87, v88 offset0:132 offset1:198
	s_waitcnt vmcnt(18)
	ds_write2_b32 v54, v89, v90 offset0:8 offset1:74
	s_waitcnt vmcnt(16)
	ds_write2_b32 v54, v91, v92 offset0:140 offset1:206
	v_add_u32_e32 v52, 0x840, v52
	v_add_u32_e32 v54, 0x400, v52
	s_waitcnt vmcnt(14)
	ds_write2_b32 v52, v93, v94 offset1:66
	s_waitcnt vmcnt(12)
	ds_write2_b32 v52, v95, v96 offset0:132 offset1:198
	s_waitcnt vmcnt(10)
	ds_write2_b32 v54, v97, v98 offset0:8 offset1:74
	s_waitcnt vmcnt(8)
	ds_write2_b32 v54, v99, v100 offset0:140 offset1:206
	v_add_u32_e32 v52, 0x840, v52
	v_add_u32_e32 v54, 0x400, v52
	s_waitcnt vmcnt(6)
	ds_write2_b32 v52, v101, v102 offset1:66
	s_waitcnt vmcnt(4)
	ds_write2_b32 v52, v103, v104 offset0:132 offset1:198
	s_waitcnt vmcnt(2)
	ds_write2_b32 v54, v105, v106 offset0:8 offset1:74
	s_waitcnt vmcnt(0)
	ds_write2_b32 v54, v107, v108 offset0:140 offset1:206
	v_add_u32_e32 v52, 0x840, v52
	s_waitcnt lgkmcnt(0)
	ds_read2_b32 v[16:17], v30 offset0:33 offset1:41
	ds_read2_b32 v[18:19], v30 offset1:8
	ds_read2_b32 v[20:21], v30 offset0:66 offset1:74
	ds_read2_b32 v[22:23], v30 offset0:99 offset1:107
	ds_read2_b32 v[24:25], v30 offset0:132 offset1:140
	ds_read2_b32 v[26:27], v30 offset0:165 offset1:173
	ds_read2_b32 v[52:53], v30 offset0:198 offset1:206
	ds_read2_b32 v[54:55], v30 offset0:231 offset1:239
	s_lshl_b32 s4, s8, 5
	s_and_b32 s4, s4, 0x7e0
	s_add_i32 s2, s6, 0xfffff580
	s_waitcnt lgkmcnt(6)
	v_cvt_pk_bf16_f32 v12, v18, v16
	v_or_b32_e32 v16, s4, v29
	v_lshl_add_u64 v[56:57], s[2:3], 1, v[2:3]
	v_lshlrev_b32_e32 v58, 11, v16
	v_mov_b32_e32 v59, v1
	s_waitcnt lgkmcnt(4)
	v_cvt_pk_bf16_f32 v13, v20, v22
	s_waitcnt lgkmcnt(2)
	v_cvt_pk_bf16_f32 v14, v24, v26
	s_waitcnt lgkmcnt(0)
	v_cvt_pk_bf16_f32 v15, v52, v54
	v_lshl_add_u64 v[58:59], v[56:57], 0, v[58:59]
	global_store_dwordx4 v[58:59], v[12:15], off
	v_or_b32_e32 v16, s4, v31
	v_lshlrev_b32_e32 v16, 11, v16
	v_cvt_pk_bf16_f32 v12, v19, v17
	v_cvt_pk_bf16_f32 v13, v21, v23
	v_cvt_pk_bf16_f32 v14, v25, v27
	v_cvt_pk_bf16_f32 v15, v53, v55
	ds_read2_b32 v[18:19], v30 offset0:49 offset1:57
	ds_read2_b32 v[20:21], v30 offset0:16 offset1:24
	ds_read2_b32 v[22:23], v30 offset0:82 offset1:90
	ds_read2_b32 v[24:25], v30 offset0:115 offset1:123
	ds_read2_b32 v[26:27], v30 offset0:148 offset1:156
	ds_read2_b32 v[52:53], v30 offset0:181 offset1:189
	ds_read2_b32 v[54:55], v30 offset0:214 offset1:222
	ds_read2_b32 v[58:59], v30 offset0:247 offset1:255
	v_mov_b32_e32 v17, v1
	v_lshl_add_u64 v[16:17], v[56:57], 0, v[16:17]
	global_store_dwordx4 v[16:17], v[12:15], off
	v_or_b32_e32 v16, s4, v32
	v_lshlrev_b32_e32 v16, 11, v16
	v_mov_b32_e32 v17, v1
	s_waitcnt lgkmcnt(6)
	v_cvt_pk_bf16_f32 v12, v20, v18
	s_waitcnt lgkmcnt(4)
	v_cvt_pk_bf16_f32 v13, v22, v24
	s_waitcnt lgkmcnt(2)
	v_cvt_pk_bf16_f32 v14, v26, v52
	s_waitcnt lgkmcnt(0)
	v_cvt_pk_bf16_f32 v15, v54, v58
	v_lshl_add_u64 v[16:17], v[56:57], 0, v[16:17]
	global_store_dwordx4 v[16:17], v[12:15], off
	v_or_b32_e32 v16, s4, v33
	v_lshlrev_b32_e32 v16, 11, v16
	v_mov_b32_e32 v17, v1
	v_cvt_pk_bf16_f32 v12, v21, v19
	v_cvt_pk_bf16_f32 v13, v23, v25
	v_cvt_pk_bf16_f32 v14, v27, v53
	v_cvt_pk_bf16_f32 v15, v55, v59
	v_lshl_add_u64 v[16:17], v[56:57], 0, v[16:17]
	global_store_dwordx4 v[16:17], v[12:15], off
	s_waitcnt lgkmcnt(0)
	s_mov_b64 s[4:5], 0

;     ...
;     for (int i = 0; i < 32; ++i) { const int kk = 2 * i + (lane >> 5); scr[kk * 33 + (lane & 31)] = __builtin_nontemporal_load(&W[(size_t)(k0 + kk) * ldw + col0 + n0 + (lane & 31)]); }
.LBB0_118:
	v_lshl_add_u64 v[24:25], v[20:21], 0, s[4:5]
	v_add_co_u32_e32 v58, vcc, 0x3000, v24
	v_lshl_add_u64 v[26:27], v[18:19], 0, s[4:5]
	s_nop 0
	v_addc_co_u32_e32 v59, vcc, 0, v25, vcc
	v_add_co_u32_e32 v60, vcc, 0x11000, v24
	v_lshl_add_u64 v[52:53], v[16:17], 0, s[4:5]
	s_nop 0
	v_addc_co_u32_e32 v61, vcc, 0, v25, vcc
	v_add_co_u32_e32 v62, vcc, 0x20000, v24
	v_lshl_add_u64 v[54:55], v[14:15], 0, s[4:5]
	s_nop 0
	v_addc_co_u32_e32 v63, vcc, 0, v25, vcc
	v_add_co_u32_e32 v24, vcc, 0x2e000, v24
	v_lshl_add_u64 v[56:57], v[12:13], 0, s[4:5]
	global_load_dword v77, v[58:59], off offset:64 nt
	global_load_dword v78, v[60:61], off offset:2240 nt
	v_addc_co_u32_e32 v25, vcc, 0, v25, vcc
	global_load_dword v79, v[62:63], off offset:320 nt
	global_load_dword v80, v[24:25], off offset:2496 nt
	global_load_dword v81, v[26:27], off nt
	global_load_dword v82, v[52:53], off nt
	global_load_dword v83, v[54:55], off nt
	global_load_dword v84, v[56:57], off nt
	s_add_u32 s4, s4, 0x74400
	s_addc_u32 s5, s5, 0
	v_lshl_add_u64 v[24:25], v[20:21], 0, s[4:5]
	v_add_co_u32_e32 v58, vcc, 0x3000, v24
	v_lshl_add_u64 v[26:27], v[18:19], 0, s[4:5]
	s_nop 0
	v_addc_co_u32_e32 v59, vcc, 0, v25, vcc
	v_add_co_u32_e32 v60, vcc, 0x11000, v24
	v_lshl_add_u64 v[52:53], v[16:17], 0, s[4:5]
	s_nop 0
	v_addc_co_u32_e32 v61, vcc, 0, v25, vcc
	v_add_co_u32_e32 v62, vcc, 0x20000, v24
	v_lshl_add_u64 v[54:55], v[14:15], 0, s[4:5]
	s_nop 0
	v_addc_co_u32_e32 v63, vcc, 0, v25, vcc
	v_add_co_u32_e32 v24, vcc, 0x2e000, v24
	v_lshl_add_u64 v[56:57], v[12:13], 0, s[4:5]
	global_load_dword v85, v[58:59], off offset:64 nt
	global_load_dword v86, v[60:61], off offset:2240 nt
	v_addc_co_u32_e32 v25, vcc, 0, v25, vcc
	global_load_dword v87, v[62:63], off offset:320 nt
	global_load_dword v88, v[24:25], off offset:2496 nt
	global_load_dword v89, v[26:27], off nt
	global_load_dword v90, v[52:53], off nt
	global_load_dword v91, v[54:55], off nt
	global_load_dword v92, v[56:57], off nt
	s_add_u32 s4, s4, 0x74400
	s_addc_u32 s5, s5, 0
	v_lshl_add_u64 v[24:25], v[20:21], 0, s[4:5]
	v_add_co_u32_e32 v58, vcc, 0x3000, v24
	v_lshl_add_u64 v[26:27], v[18:19], 0, s[4:5]
	s_nop 0
	v_addc_co_u32_e32 v59, vcc, 0, v25, vcc
	v_add_co_u32_e32 v60, vcc, 0x11000, v24
	v_lshl_add_u64 v[52:53], v[16:17], 0, s[4:5]
	s_nop 0
	v_addc_co_u32_e32 v61, vcc, 0, v25, vcc
	v_add_co_u32_e32 v62, vcc, 0x20000, v24
	v_lshl_add_u64 v[54:55], v[14:15], 0, s[4:5]
	s_nop 0
	v_addc_co_u32_e32 v63, vcc, 0, v25, vcc
	v_add_co_u32_e32 v24, vcc, 0x2e000, v24
	v_lshl_add_u64 v[56:57], v[12:13], 0, s[4:5]
	global_load_dword v93, v[58:59], off offset:64 nt
	global_load_dword v94, v[60:61], off offset:2240 nt
	v_addc_co_u32_e32 v25, vcc, 0, v25, vcc
	global_load_dword v95, v[62:63], off offset:320 nt
	global_load_dword v96, v[24:25], off offset:2496 nt
	global_load_dword v97, v[26:27], off nt
	global_load_dword v98, v[52:53], off nt
	global_load_dword v99, v[54:55], off nt
	global_load_dword v100, v[56:57], off nt
	s_add_u32 s4, s4, 0x74400
	s_addc_u32 s5, s5, 0
	v_lshl_add_u64 v[24:25], v[20:21], 0, s[4:5]
	v_add_co_u32_e32 v58, vcc, 0x3000, v24
	v_lshl_add_u64 v[26:27], v[18:19], 0, s[4:5]
	s_nop 0
	v_addc_co_u32_e32 v59, vcc, 0, v25, vcc
	v_add_co_u32_e32 v60, vcc, 0x11000, v24
	v_lshl_add_u64 v[52:53], v[16:17], 0, s[4:5]
	s_nop 0
	v_addc_co_u32_e32 v61, vcc, 0, v25, vcc
	v_add_co_u32_e32 v62, vcc, 0x20000, v24
	v_lshl_add_u64 v[54:55], v[14:15], 0, s[4:5]
	s_nop 0
	v_addc_co_u32_e32 v63, vcc, 0, v25, vcc
	v_add_co_u32_e32 v24, vcc, 0x2e000, v24
	v_lshl_add_u64 v[56:57], v[12:13], 0, s[4:5]
	global_load_dword v101, v[58:59], off offset:64 nt
	global_load_dword v102, v[60:61], off offset:2240 nt
	v_addc_co_u32_e32 v25, vcc, 0, v25, vcc
	global_load_dword v103, v[62:63], off offset:320 nt
	global_load_dword v104, v[24:25], off offset:2496 nt
	global_load_dword v105, v[26:27], off nt
	global_load_dword v106, v[52:53], off nt
	global_load_dword v107, v[54:55], off nt
	global_load_dword v108, v[56:57], off nt
	s_add_u32 s4, s4, 0x74400
	s_addc_u32 s5, s5, 0
	v_add_u32_e32 v24, 0x400, v22
	s_waitcnt vmcnt(30)
	ds_write2_b32 v22, v77, v78 offset1:66
	s_waitcnt vmcnt(28)
; #define LAS __attribute__((address_space(3)))
; __device__ __forceinline__ unsigned pk2(float lo, float hi) { const f32x2 v = {lo, hi}; return __builtin_bit_cast(unsigned, __builtin_convertvector(v, bf16x2_hw)); }
;     ...
;     for (int i = 0; i < 32; ++i) { const int kk = 2 * i + (lane >> 5); scr[kk * 33 + (lane & 31)] = __builtin_nontemporal_load(&W[(size_t)(k0 + kk) * ldw + col0 + n0 + (lane & 31)]); }
;     asm volatile("s_waitcnt lgkmcnt(0)" ::: "memory");
;     const int c = lane & 7;
; #pragma unroll
;     for (int j = 0; j < 4; ++j) { const int n = (lane >> 3) + 8 * j; const LAS float* s = scr + (8 * c) * 33 + n;
;         u32x4 o; o.x = pk2(s[0 * 33], s[1 * 33]); o.y = pk2(s[2 * 33], s[3 * 33]); o.z = pk2(s[4 * 33], s[5 * 33]); o.w = pk2(s[6 * 33], s[7 * 33]);
;         const int drow = perm ? (drow0 + 8 * (n >> 2) + (n & 3) + (d0 ? 4 : 0)) : (drow0 + n);
;         *(u32x4*)(WT + (size_t)drow * K + k0 + 8 * c) = o; }
	ds_write2_b32 v22, v79, v80 offset0:132 offset1:198
	s_waitcnt vmcnt(26)
	ds_write2_b32 v24, v81, v82 offset0:8 offset1:74
	s_waitcnt vmcnt(24)
	ds_write2_b32 v24, v83, v84 offset0:140 offset1:206
	v_add_u32_e32 v22, 0x840, v22
	v_add_u32_e32 v24, 0x400, v22
	s_waitcnt vmcnt(22)
	ds_write2_b32 v22, v85, v86 offset1:66
	s_waitcnt vmcnt(20)
	ds_write2_b32 v22, v87, v88 offset0:132 offset1:198
	s_waitcnt vmcnt(18)
	ds_write2_b32 v24, v89, v90 offset0:8 offset1:74
	s_waitcnt vmcnt(16)
	ds_write2_b32 v24, v91, v92 offset0:140 offset1:206
	v_add_u32_e32 v22, 0x840, v22
	v_add_u32_e32 v24, 0x400, v22
	s_waitcnt vmcnt(14)
	ds_write2_b32 v22, v93, v94 offset1:66
	s_waitcnt vmcnt(12)
	ds_write2_b32 v22, v95, v96 offset0:132 offset1:198
	s_waitcnt vmcnt(10)
	ds_write2_b32 v24, v97, v98 offset0:8 offset1:74
	s_waitcnt vmcnt(8)
	ds_write2_b32 v24, v99, v100 offset0:140 offset1:206
	v_add_u32_e32 v22, 0x840, v22
	v_add_u32_e32 v24, 0x400, v22
	s_waitcnt vmcnt(6)
	ds_write2_b32 v22, v101, v102 offset1:66
	s_waitcnt vmcnt(4)
	ds_write2_b32 v22, v103, v104 offset0:132 offset1:198
	s_waitcnt vmcnt(2)
	ds_write2_b32 v24, v105, v106 offset0:8 offset1:74
	s_waitcnt vmcnt(0)
	ds_write2_b32 v24, v107, v108 offset0:140 offset1:206
	v_add_u32_e32 v22, 0x840, v22
	s_and_b32 s12, 0xffff, s12
	s_and_b32 s2, s12, 0x7c0
	s_and_b32 s4, 0xffff, s7
	s_cmp_gt_u32 s4, 47
	s_cselect_b64 vcc, -1, 0
	s_and_b64 s[4:5], vcc, exec
	s_cselect_b32 s2, s12, s2
	s_add_i32 s4, s2, 0xc00
	s_and_b32 s2, 0xffff, s6
	s_lshl_b32 s2, s2, 1
	s_waitcnt lgkmcnt(0)
	v_lshl_add_u64 v[16:17], v[4:5], 0, s[2:3]
	s_lshr_b32 s2, s12, 3
	v_and_or_b32 v12, s2, 4, v34
	ds_read2_b32 v[18:19], v30 offset0:33 offset1:41
	ds_read2_b32 v[20:21], v30 offset1:8
	ds_read2_b32 v[22:23], v30 offset0:66 offset1:74
	ds_read2_b32 v[24:25], v30 offset0:99 offset1:107
	ds_read2_b32 v[26:27], v30 offset0:132 offset1:140
	ds_read2_b32 v[52:53], v30 offset0:165 offset1:173
	ds_read2_b32 v[54:55], v30 offset0:198 offset1:206
	ds_read2_b32 v[56:57], v30 offset0:231 offset1:239
	v_or_b32_e32 v60, s4, v12
	s_waitcnt lgkmcnt(6)
	v_cvt_pk_bf16_f32 v12, v20, v18
	v_or_b32_e32 v18, v60, v35
	v_or_b32_e32 v20, s4, v29
	v_cndmask_b32_e32 v18, v18, v20, vcc
	v_lshlrev_b32_e32 v58, 11, v18
	v_mov_b32_e32 v59, v1
	s_waitcnt lgkmcnt(4)
	v_cvt_pk_bf16_f32 v13, v22, v24
	s_waitcnt lgkmcnt(2)
	v_cvt_pk_bf16_f32 v14, v26, v52
	s_waitcnt lgkmcnt(0)
	v_cvt_pk_bf16_f32 v15, v54, v56
	v_lshl_add_u64 v[58:59], v[16:17], 0, v[58:59]
	global_store_dwordx4 v[58:59], v[12:15], off
	v_or_b32_e32 v18, v60, v36
	s_nop 0
	v_cvt_pk_bf16_f32 v12, v21, v19
	v_or_b32_e32 v19, s4, v31
	v_cndmask_b32_e32 v18, v18, v19, vcc
	v_cvt_pk_bf16_f32 v13, v23, v25
	v_cvt_pk_bf16_f32 v14, v27, v53
	v_cvt_pk_bf16_f32 v15, v55, v57
	v_lshlrev_b32_e32 v18, 11, v18
	v_mov_b32_e32 v19, v1
	ds_read2_b32 v[20:21], v30 offset0:49 offset1:57
	ds_read2_b32 v[22:23], v30 offset0:16 offset1:24
	ds_read2_b32 v[24:25], v30 offset0:82 offset1:90
	ds_read2_b32 v[26:27], v30 offset0:115 offset1:123
	ds_read2_b32 v[52:53], v30 offset0:148 offset1:156
	ds_read2_b32 v[54:55], v30 offset0:181 offset1:189
	ds_read2_b32 v[56:57], v30 offset0:214 offset1:222
	ds_read2_b32 v[58:59], v30 offset0:247 offset1:255
	v_lshl_add_u64 v[18:19], v[16:17], 0, v[18:19]
	global_store_dwordx4 v[18:19], v[12:15], off
	v_add_u32_e32 v18, v60, v37
	v_or_b32_e32 v19, s4, v32
	v_cndmask_b32_e32 v18, v18, v19, vcc
	v_lshlrev_b32_e32 v18, 11, v18
	v_mov_b32_e32 v19, v1
	s_waitcnt lgkmcnt(6)
	v_cvt_pk_bf16_f32 v12, v22, v20
	s_waitcnt lgkmcnt(4)
	v_cvt_pk_bf16_f32 v13, v24, v26
	s_waitcnt lgkmcnt(2)
	v_cvt_pk_bf16_f32 v14, v52, v54
	s_waitcnt lgkmcnt(0)
	v_cvt_pk_bf16_f32 v15, v56, v58
	v_lshl_add_u64 v[18:19], v[16:17], 0, v[18:19]
	global_store_dwordx4 v[18:19], v[12:15], off
	v_add_u32_e32 v18, v60, v38
	v_or_b32_e32 v19, s4, v33
	v_cndmask_b32_e32 v18, v18, v19, vcc
	v_lshlrev_b32_e32 v18, 11, v18
	v_mov_b32_e32 v19, v1
	v_cvt_pk_bf16_f32 v12, v23, v21
	v_cvt_pk_bf16_f32 v13, v25, v27
	v_cvt_pk_bf16_f32 v14, v53, v55
	v_cvt_pk_bf16_f32 v15, v57, v59
	v_lshl_add_u64 v[16:17], v[16:17], 0, v[18:19]
	global_store_dwordx4 v[16:17], v[12:15], off
	s_waitcnt lgkmcnt(0)

;     ...
;     for (int i = 0; i < 32; ++i) { const int kk = 2 * i + (lane >> 5); scr[kk * 33 + (lane & 31)] = __builtin_nontemporal_load(&W[(size_t)(k0 + kk) * ldw + col0 + n0 + (lane & 31)]); }
.LBB0_122:
	v_add_u32_e32 v18, s2, v14
	v_mad_i64_i32 v[16:17], s[12:13], v18, s11, v[12:13]
	v_add_u32_e32 v19, 2, v18
	v_add_u32_e32 v20, 4, v18
	v_add_u32_e32 v22, 6, v18
	v_add_u32_e32 v24, 8, v18
	v_add_u32_e32 v26, 10, v18
	v_add_u32_e32 v52, 12, v18
	v_add_u32_e32 v54, 14, v18
	v_mad_i64_i32 v[18:19], s[12:13], v19, s11, v[12:13]
	v_mad_i64_i32 v[20:21], s[12:13], v20, s11, v[12:13]
	v_mad_i64_i32 v[22:23], s[12:13], v22, s11, v[12:13]
	v_mad_i64_i32 v[24:25], s[12:13], v24, s11, v[12:13]
	v_mad_i64_i32 v[26:27], s[12:13], v26, s11, v[12:13]
	v_mad_i64_i32 v[52:53], s[12:13], v52, s11, v[12:13]
	v_mad_i64_i32 v[54:55], s[12:13], v54, s11, v[12:13]
	global_load_dword v77, v[16:17], off nt
	global_load_dword v78, v[18:19], off nt
	global_load_dword v79, v[20:21], off nt
	global_load_dword v80, v[22:23], off nt
	global_load_dword v81, v[24:25], off nt
	global_load_dword v82, v[26:27], off nt
	global_load_dword v83, v[52:53], off nt
	global_load_dword v84, v[54:55], off nt
	s_add_i32 s2, s2, 16
	v_add_u32_e32 v18, s2, v14
	v_mad_i64_i32 v[16:17], s[12:13], v18, s11, v[12:13]
	v_add_u32_e32 v19, 2, v18
	v_add_u32_e32 v20, 4, v18
	v_add_u32_e32 v22, 6, v18
	v_add_u32_e32 v24, 8, v18
	v_add_u32_e32 v26, 10, v18
	v_add_u32_e32 v52, 12, v18
	v_add_u32_e32 v54, 14, v18
	v_mad_i64_i32 v[18:19], s[12:13], v19, s11, v[12:13]
	v_mad_i64_i32 v[20:21], s[12:13], v20, s11, v[12:13]
	v_mad_i64_i32 v[22:23], s[12:13], v22, s11, v[12:13]
	v_mad_i64_i32 v[24:25], s[12:13], v24, s11, v[12:13]
	v_mad_i64_i32 v[26:27], s[12:13], v26, s11, v[12:13]
	v_mad_i64_i32 v[52:53], s[12:13], v52, s11, v[12:13]
	v_mad_i64_i32 v[54:55], s[12:13], v54, s11, v[12:13]
	global_load_dword v85, v[16:17], off nt
	global_load_dword v86, v[18:19], off nt
	global_load_dword v87, v[20:21], off nt
	global_load_dword v88, v[22:23], off nt
	global_load_dword v89, v[24:25], off nt
	global_load_dword v90, v[26:27], off nt
	global_load_dword v91, v[52:53], off nt
	global_load_dword v92, v[54:55], off nt
	s_add_i32 s2, s2, 16
	v_add_u32_e32 v18, s2, v14
	v_mad_i64_i32 v[16:17], s[12:13], v18, s11, v[12:13]
	v_add_u32_e32 v19, 2, v18
	v_add_u32_e32 v20, 4, v18
	v_add_u32_e32 v22, 6, v18
	v_add_u32_e32 v24, 8, v18
	v_add_u32_e32 v26, 10, v18
	v_add_u32_e32 v52, 12, v18
	v_add_u32_e32 v54, 14, v18
	v_mad_i64_i32 v[18:19], s[12:13], v19, s11, v[12:13]
	v_mad_i64_i32 v[20:21], s[12:13], v20, s11, v[12:13]
	v_mad_i64_i32 v[22:23], s[12:13], v22, s11, v[12:13]
	v_mad_i64_i32 v[24:25], s[12:13], v24, s11, v[12:13]
	v_mad_i64_i32 v[26:27], s[12:13], v26, s11, v[12:13]
	v_mad_i64_i32 v[52:53], s[12:13], v52, s11, v[12:13]
	v_mad_i64_i32 v[54:55], s[12:13], v54, s11, v[12:13]
	global_load_dword v93, v[16:17], off nt
	global_load_dword v94, v[18:19], off nt
	global_load_dword v95, v[20:21], off nt
	global_load_dword v96, v[22:23], off nt
	global_load_dword v97, v[24:25], off nt
	global_load_dword v98, v[26:27], off nt
	global_load_dword v99, v[52:53], off nt
	global_load_dword v100, v[54:55], off nt
	s_add_i32 s2, s2, 16
	v_add_u32_e32 v18, s2, v14
	v_mad_i64_i32 v[16:17], s[12:13], v18, s11, v[12:13]
	v_add_u32_e32 v19, 2, v18
	v_add_u32_e32 v20, 4, v18
	v_add_u32_e32 v22, 6, v18
	v_add_u32_e32 v24, 8, v18
	v_add_u32_e32 v26, 10, v18
	v_add_u32_e32 v52, 12, v18
	v_add_u32_e32 v54, 14, v18
	v_mad_i64_i32 v[18:19], s[12:13], v19, s11, v[12:13]
	v_mad_i64_i32 v[20:21], s[12:13], v20, s11, v[12:13]
	v_mad_i64_i32 v[22:23], s[12:13], v22, s11, v[12:13]
	v_mad_i64_i32 v[24:25], s[12:13], v24, s11, v[12:13]
	v_mad_i64_i32 v[26:27], s[12:13], v26, s11, v[12:13]
	v_mad_i64_i32 v[52:53], s[12:13], v52, s11, v[12:13]
	v_mad_i64_i32 v[54:55], s[12:13], v54, s11, v[12:13]
	global_load_dword v101, v[16:17], off nt
	global_load_dword v102, v[18:19], off nt
	global_load_dword v103, v[20:21], off nt
	global_load_dword v104, v[22:23], off nt
	global_load_dword v105, v[24:25], off nt
	global_load_dword v106, v[26:27], off nt
	global_load_dword v107, v[52:53], off nt
	global_load_dword v108, v[54:55], off nt
	s_add_i32 s2, s2, 16
	v_add_u32_e32 v16, 0x400, v15
	s_waitcnt vmcnt(30)
; #define LAS __attribute__((address_space(3)))
; __device__ __forceinline__ unsigned pk2(float lo, float hi) { const f32x2 v = {lo, hi}; return __builtin_bit_cast(unsigned, __builtin_convertvector(v, bf16x2_hw)); }
;     ...
;     for (int i = 0; i < 32; ++i) { const int kk = 2 * i + (lane >> 5); scr[kk * 33 + (lane & 31)] = __builtin_nontemporal_load(&W[(size_t)(k0 + kk) * ldw + col0 + n0 + (lane & 31)]); }
;     asm volatile("s_waitcnt lgkmcnt(0)" ::: "memory");
;     const int c = lane & 7;
; #pragma unroll
;     for (int j = 0; j < 4; ++j) { const int n = (lane >> 3) + 8 * j; const LAS float* s = scr + (8 * c) * 33 + n;
;         u32x4 o; o.x = pk2(s[0 * 33], s[1 * 33]); o.y = pk2(s[2 * 33], s[3 * 33]); o.z = pk2(s[4 * 33], s[5 * 33]); o.w = pk2(s[6 * 33], s[7 * 33]);
;         const int drow = perm ? (drow0 + 8 * (n >> 2) + (n & 3) + (d0 ? 4 : 0)) : (drow0 + n);
;         *(u32x4*)(WT + (size_t)drow * K + k0 + 8 * c) = o; }
;     asm volatile("s_waitcnt lgkmcnt(0)" ::: "memory");
; __device__ __forceinline__ void phase0_transposes(const Ctx& X, KArgs a, int it0, int it1, int gw, int ngw) {
;     ...
;     for (int it = it0 + gw; it < (it1 < 0 ? NITEMS : it1); it += ngw) {
	ds_write2_b32 v15, v77, v78 offset1:66
	s_waitcnt vmcnt(28)
	ds_write2_b32 v15, v79, v80 offset0:132 offset1:198
	s_waitcnt vmcnt(26)
	ds_write2_b32 v16, v81, v82 offset0:8 offset1:74
	s_waitcnt vmcnt(24)
	ds_write2_b32 v16, v83, v84 offset0:140 offset1:206
	v_add_u32_e32 v15, 0x840, v15
	v_add_u32_e32 v16, 0x400, v15
	s_waitcnt vmcnt(22)
	ds_write2_b32 v15, v85, v86 offset1:66
	s_waitcnt vmcnt(20)
	ds_write2_b32 v15, v87, v88 offset0:132 offset1:198
	s_waitcnt vmcnt(18)
	ds_write2_b32 v16, v89, v90 offset0:8 offset1:74
	s_waitcnt vmcnt(16)
	ds_write2_b32 v16, v91, v92 offset0:140 offset1:206
	v_add_u32_e32 v15, 0x840, v15
	v_add_u32_e32 v16, 0x400, v15
	s_waitcnt vmcnt(14)
	ds_write2_b32 v15, v93, v94 offset1:66
	s_waitcnt vmcnt(12)
	ds_write2_b32 v15, v95, v96 offset0:132 offset1:198
	s_waitcnt vmcnt(10)
	ds_write2_b32 v16, v97, v98 offset0:8 offset1:74
	s_waitcnt vmcnt(8)
	ds_write2_b32 v16, v99, v100 offset0:140 offset1:206
	v_add_u32_e32 v15, 0x840, v15
	v_add_u32_e32 v16, 0x400, v15
	s_waitcnt vmcnt(6)
	ds_write2_b32 v15, v101, v102 offset1:66
	s_waitcnt vmcnt(4)
	ds_write2_b32 v15, v103, v104 offset0:132 offset1:198
	s_waitcnt vmcnt(2)
	ds_write2_b32 v16, v105, v106 offset0:8 offset1:74
	s_waitcnt vmcnt(0)
	ds_write2_b32 v16, v107, v108 offset0:140 offset1:206
	v_add_u32_e32 v15, 0x840, v15
	s_waitcnt lgkmcnt(0)
	ds_read2_b32 v[16:17], v30 offset0:33 offset1:41
	ds_read2_b32 v[18:19], v30 offset1:8
	ds_read2_b32 v[20:21], v30 offset0:66 offset1:74
	ds_read2_b32 v[22:23], v30 offset0:99 offset1:107
	ds_read2_b32 v[24:25], v30 offset0:132 offset1:140
	ds_read2_b32 v[26:27], v30 offset0:165 offset1:173
	ds_read2_b32 v[52:53], v30 offset0:198 offset1:206
	ds_read2_b32 v[54:55], v30 offset0:231 offset1:239
	v_or_b32_e32 v58, s4, v29
	s_ashr_i32 s7, s6, 31
	v_ashrrev_i32_e32 v59, 31, v58
	v_lshl_add_u64 v[56:57], s[6:7], 1, v[4:5]
	v_lshlrev_b64 v[58:59], 11, v[58:59]
	s_waitcnt lgkmcnt(6)
	v_cvt_pk_bf16_f32 v12, v18, v16
	s_waitcnt lgkmcnt(4)
	v_cvt_pk_bf16_f32 v13, v20, v22
	s_waitcnt lgkmcnt(2)
	v_cvt_pk_bf16_f32 v14, v24, v26
	s_waitcnt lgkmcnt(0)
	v_cvt_pk_bf16_f32 v15, v52, v54
	v_lshl_add_u64 v[58:59], v[56:57], 0, v[58:59]
	v_or_b32_e32 v16, s4, v31
	global_store_dwordx4 v[58:59], v[12:15], off
	s_nop 1
	v_cvt_pk_bf16_f32 v12, v19, v17
	v_ashrrev_i32_e32 v17, 31, v16
	v_cvt_pk_bf16_f32 v13, v21, v23
	v_cvt_pk_bf16_f32 v14, v25, v27
	v_cvt_pk_bf16_f32 v15, v53, v55
	v_lshlrev_b64 v[16:17], 11, v[16:17]
	ds_read2_b32 v[18:19], v30 offset0:49 offset1:57
	ds_read2_b32 v[20:21], v30 offset0:16 offset1:24
	ds_read2_b32 v[22:23], v30 offset0:82 offset1:90
	ds_read2_b32 v[24:25], v30 offset0:115 offset1:123
	ds_read2_b32 v[26:27], v30 offset0:148 offset1:156
	ds_read2_b32 v[52:53], v30 offset0:181 offset1:189
	ds_read2_b32 v[54:55], v30 offset0:214 offset1:222
	ds_read2_b32 v[58:59], v30 offset0:247 offset1:255
	v_lshl_add_u64 v[16:17], v[56:57], 0, v[16:17]
	global_store_dwordx4 v[16:17], v[12:15], off
	v_or_b32_e32 v16, s4, v32
	v_ashrrev_i32_e32 v17, 31, v16
	v_lshlrev_b64 v[16:17], 11, v[16:17]
	s_waitcnt lgkmcnt(6)
	v_cvt_pk_bf16_f32 v12, v20, v18
	s_waitcnt lgkmcnt(4)
	v_cvt_pk_bf16_f32 v13, v22, v24
	s_waitcnt lgkmcnt(2)
	v_cvt_pk_bf16_f32 v14, v26, v52
	s_waitcnt lgkmcnt(0)
	v_cvt_pk_bf16_f32 v15, v54, v58
	v_lshl_add_u64 v[16:17], v[56:57], 0, v[16:17]
	global_store_dwordx4 v[16:17], v[12:15], off
	v_or_b32_e32 v16, s4, v33
	v_ashrrev_i32_e32 v17, 31, v16
	v_lshlrev_b64 v[16:17], 11, v[16:17]
	v_cvt_pk_bf16_f32 v12, v21, v19
	v_cvt_pk_bf16_f32 v13, v23, v25
	v_cvt_pk_bf16_f32 v14, v27, v53
	v_cvt_pk_bf16_f32 v15, v55, v59
	v_lshl_add_u64 v[16:17], v[56:57], 0, v[16:17]
	global_store_dwordx4 v[16:17], v[12:15], off
	s_waitcnt lgkmcnt(0)
	s_branch .LBB0_109
